# phase0 weight transposes: 16 row loads issued back-to-back with one wait instead of load-wait per row
# speedup vs baseline: 1.0395x; 1.0395x over previous
; DI int otid() { int t = threadIdx.x; asm volatile("" : "+v"(t)); return t; }
; DI int winmap(int np) {
;   if (np < 2048) return np;
;   if (np < 4096) return np + 8;
;   int j = np - 4096;
;   return j < 8 ? 2048 + j : 4104 + (j - 8);
; }
; DI void transpose_tile(const float* __restrict__ W, int K, int N, bf16_t* __restrict__ Wt, int Np, int kt, int nt,
;                        int mode, float* sm) {
;   const int tid = otid();
;   const int tx = tid & 63, ty = tid >> 6;
; #pragma unroll 4
;   for (int i = 0; i < 16; ++i) {
;     int k = ty + 4 * i;
;     int np = nt * 64 + tx;
;     float v = 0.f;
;     if (np < Np) {
;       int n = mode ? winmap(np) : np;
;       v = W[(size_t)(kt * 64 + k) * N + n];
;     }
;     sm[k * 65 + tx] = v;
;   }
.LBB0_22:
	s_mul_hi_i32 s4, s12, 0x7e07e07f
	s_lshr_b32 s5, s4, 31
	s_ashr_i32 s4, s4, 5
	s_add_i32 s6, s4, s5
	s_mul_i32 s4, s6, 0x41
	s_sub_i32 s4, s12, s4
	v_mov_b32_e32 v0, v192
	s_lshl_b32 s13, s4, 6
	v_and_b32_e32 v4, 63, v0
	v_ashrrev_i32_e32 v5, 6, v0
	v_or_b32_e32 v0, s13, v4
	s_cmpk_lt_u32 s13, 0x1000
	v_add_u32_e32 v2, 0xfffff800, v0
	v_cmp_gt_u32_e64 s[4:5], s3, v0
	v_add_u32_e32 v3, 8, v0
	v_cmp_gt_i32_e32 vcc, s0, v0
	v_cndmask_b32_e64 v2, v0, v2, s[4:5]
	s_cselect_b64 s[4:5], -1, 0
	v_cndmask_b32_e64 v2, v2, v3, s[4:5]
	v_cmp_gt_i32_e64 s[4:5], s1, v0
	s_lshl_b32 s6, s6, 6
	v_add_u32_e32 v6, s6, v5
	v_cndmask_b32_e64 v2, v2, v0, s[4:5]
	v_ashrrev_i32_e32 v3, 31, v2
	v_mul_lo_u32 v0, v5, s10
	v_lshl_add_u64 v[2:3], v[2:3], 2, s[74:75]
	v_lshl_add_u32 v0, v4, 2, v0
	v_mov_b32_e32 v10, 0
	v_mov_b32_e32 v11, 0
	v_mov_b32_e32 v12, 0
	v_mov_b32_e32 v13, 0
	v_mov_b32_e32 v14, 0
	v_mov_b32_e32 v15, 0
	v_mov_b32_e32 v16, 0
	v_mov_b32_e32 v17, 0
	v_mov_b32_e32 v18, 0
	v_mov_b32_e32 v19, 0
	v_mov_b32_e32 v20, 0
	v_mov_b32_e32 v21, 0
	v_mov_b32_e32 v22, 0
	v_mov_b32_e32 v23, 0
	v_mov_b32_e32 v24, 0
	v_mov_b32_e32 v25, 0
	s_and_saveexec_b64 s[100:101], vcc
	s_mov_b32 s98, 0x4040
	v_mad_u64_u32 v[8:9], vcc, v6, s98, v[2:3]
	s_mov_b32 s98, 0x10100
	s_mov_b32 s99, 0
	global_load_dword v10, v[8:9], off
	v_lshl_add_u64 v[8:9], v[8:9], 0, s[98:99]
	global_load_dword v11, v[8:9], off
	v_lshl_add_u64 v[8:9], v[8:9], 0, s[98:99]
	global_load_dword v12, v[8:9], off
	v_lshl_add_u64 v[8:9], v[8:9], 0, s[98:99]
	global_load_dword v13, v[8:9], off
	v_lshl_add_u64 v[8:9], v[8:9], 0, s[98:99]
	global_load_dword v14, v[8:9], off
	v_lshl_add_u64 v[8:9], v[8:9], 0, s[98:99]
	global_load_dword v15, v[8:9], off
	v_lshl_add_u64 v[8:9], v[8:9], 0, s[98:99]
	global_load_dword v16, v[8:9], off
	v_lshl_add_u64 v[8:9], v[8:9], 0, s[98:99]
	global_load_dword v17, v[8:9], off
	v_lshl_add_u64 v[8:9], v[8:9], 0, s[98:99]
	global_load_dword v18, v[8:9], off
	v_lshl_add_u64 v[8:9], v[8:9], 0, s[98:99]
	global_load_dword v19, v[8:9], off
	v_lshl_add_u64 v[8:9], v[8:9], 0, s[98:99]
	global_load_dword v20, v[8:9], off
	v_lshl_add_u64 v[8:9], v[8:9], 0, s[98:99]
	global_load_dword v21, v[8:9], off
	v_lshl_add_u64 v[8:9], v[8:9], 0, s[98:99]
	global_load_dword v22, v[8:9], off
	v_lshl_add_u64 v[8:9], v[8:9], 0, s[98:99]
	global_load_dword v23, v[8:9], off
	v_lshl_add_u64 v[8:9], v[8:9], 0, s[98:99]
	global_load_dword v24, v[8:9], off
	v_lshl_add_u64 v[8:9], v[8:9], 0, s[98:99]
	global_load_dword v25, v[8:9], off
	s_or_b64 exec, exec, s[100:101]
	s_waitcnt vmcnt(0)
	ds_write_b32 v0, v10
	ds_write_b32 v0, v11 offset:1040
	ds_write_b32 v0, v12 offset:2080
	ds_write_b32 v0, v13 offset:3120
	ds_write_b32 v0, v14 offset:4160
	ds_write_b32 v0, v15 offset:5200
	ds_write_b32 v0, v16 offset:6240
	ds_write_b32 v0, v17 offset:7280
	ds_write_b32 v0, v18 offset:8320
	ds_write_b32 v0, v19 offset:9360
	ds_write_b32 v0, v20 offset:10400
	ds_write_b32 v0, v21 offset:11440
	ds_write_b32 v0, v22 offset:12480
	ds_write_b32 v0, v23 offset:13520
	ds_write_b32 v0, v24 offset:14560
	ds_write_b32 v0, v25 offset:15600

; DI int otid() { int t = threadIdx.x; asm volatile("" : "+v"(t)); return t; }
; DI void transpose_tile(const float* __restrict__ W, int K, int N, bf16_t* __restrict__ Wt, int Np, int kt, int nt,
;                        int mode, float* sm) {
;   const int tid = otid();
;   const int tx = tid & 63, ty = tid >> 6;
; #pragma unroll 4
;   for (int i = 0; i < 16; ++i) {
;     int k = ty + 4 * i;
;     int np = nt * 64 + tx;
;     float v = 0.f;
;     if (np < Np) {
;       int n = mode ? winmap(np) : np;
;       v = W[(size_t)(kt * 64 + k) * N + n];
;     }
;     sm[k * 65 + tx] = v;
;   }
.LBB0_45:
	s_ashr_i32 s4, s3, 31
	s_lshr_b32 s4, s4, 28
	s_add_i32 s4, s3, s4
	s_and_b32 s5, s4, 0x3fffff0
	s_sub_i32 s5, s3, s5
	v_mov_b32_e32 v0, v192
	s_lshl_b32 s12, s5, 6
	v_and_b32_e32 v4, 63, v0
	v_ashrrev_i32_e32 v5, 6, v0
	v_or_b32_e32 v2, s12, v4
	s_lshl_b32 s4, s4, 2
	s_andn2_b32 s4, s4, 63
	v_ashrrev_i32_e32 v3, 31, v2
	v_mul_lo_u32 v0, v5, s1
	v_cmp_gt_i32_e32 vcc, s0, v2
	v_lshl_add_u64 v[2:3], v[2:3], 2, s[60:61]
	v_lshl_add_u32 v0, v4, 2, v0
	v_add_u32_e32 v6, s4, v5
	v_mov_b32_e32 v10, 0
	v_mov_b32_e32 v11, 0
	v_mov_b32_e32 v12, 0
	v_mov_b32_e32 v13, 0
	v_mov_b32_e32 v14, 0
	v_mov_b32_e32 v15, 0
	v_mov_b32_e32 v16, 0
	v_mov_b32_e32 v17, 0
	v_mov_b32_e32 v18, 0
	v_mov_b32_e32 v19, 0
	v_mov_b32_e32 v20, 0
	v_mov_b32_e32 v21, 0
	v_mov_b32_e32 v22, 0
	v_mov_b32_e32 v23, 0
	v_mov_b32_e32 v24, 0
	v_mov_b32_e32 v25, 0
	s_and_saveexec_b64 s[100:101], vcc
	s_mov_b32 s98, 0x1000
	v_mad_u64_u32 v[8:9], vcc, v6, s98, v[2:3]
	s_mov_b32 s98, 0x4000
	s_mov_b32 s99, 0
	global_load_dword v10, v[8:9], off
	v_lshl_add_u64 v[8:9], v[8:9], 0, s[98:99]
	global_load_dword v11, v[8:9], off
	v_lshl_add_u64 v[8:9], v[8:9], 0, s[98:99]
	global_load_dword v12, v[8:9], off
	v_lshl_add_u64 v[8:9], v[8:9], 0, s[98:99]
	global_load_dword v13, v[8:9], off
	v_lshl_add_u64 v[8:9], v[8:9], 0, s[98:99]
	global_load_dword v14, v[8:9], off
	v_lshl_add_u64 v[8:9], v[8:9], 0, s[98:99]
	global_load_dword v15, v[8:9], off
	v_lshl_add_u64 v[8:9], v[8:9], 0, s[98:99]
	global_load_dword v16, v[8:9], off
	v_lshl_add_u64 v[8:9], v[8:9], 0, s[98:99]
	global_load_dword v17, v[8:9], off
	v_lshl_add_u64 v[8:9], v[8:9], 0, s[98:99]
	global_load_dword v18, v[8:9], off
	v_lshl_add_u64 v[8:9], v[8:9], 0, s[98:99]
	global_load_dword v19, v[8:9], off
	v_lshl_add_u64 v[8:9], v[8:9], 0, s[98:99]
	global_load_dword v20, v[8:9], off
	v_lshl_add_u64 v[8:9], v[8:9], 0, s[98:99]
	global_load_dword v21, v[8:9], off
	v_lshl_add_u64 v[8:9], v[8:9], 0, s[98:99]
	global_load_dword v22, v[8:9], off
	v_lshl_add_u64 v[8:9], v[8:9], 0, s[98:99]
	global_load_dword v23, v[8:9], off
	v_lshl_add_u64 v[8:9], v[8:9], 0, s[98:99]
	global_load_dword v24, v[8:9], off
	v_lshl_add_u64 v[8:9], v[8:9], 0, s[98:99]
	global_load_dword v25, v[8:9], off
	s_or_b64 exec, exec, s[100:101]
	s_waitcnt vmcnt(0)
	ds_write_b32 v0, v10
	ds_write_b32 v0, v11 offset:1040
	ds_write_b32 v0, v12 offset:2080
	ds_write_b32 v0, v13 offset:3120
	ds_write_b32 v0, v14 offset:4160
	ds_write_b32 v0, v15 offset:5200
	ds_write_b32 v0, v16 offset:6240
	ds_write_b32 v0, v17 offset:7280
	ds_write_b32 v0, v18 offset:8320
	ds_write_b32 v0, v19 offset:9360
	ds_write_b32 v0, v20 offset:10400
	ds_write_b32 v0, v21 offset:11440
	ds_write_b32 v0, v22 offset:12480
	ds_write_b32 v0, v23 offset:13520
	ds_write_b32 v0, v24 offset:14560
	ds_write_b32 v0, v25 offset:15600

; DI int otid() { int t = threadIdx.x; asm volatile("" : "+v"(t)); return t; }
; DI void transpose_tile(const float* __restrict__ W, int K, int N, bf16_t* __restrict__ Wt, int Np, int kt, int nt,
;                        int mode, float* sm) {
;   const int tid = otid();
;   const int tx = tid & 63, ty = tid >> 6;
; #pragma unroll 4
;   for (int i = 0; i < 16; ++i) {
;     int k = ty + 4 * i;
;     int np = nt * 64 + tx;
;     float v = 0.f;
;     if (np < Np) {
;       int n = mode ? winmap(np) : np;
;       v = W[(size_t)(kt * 64 + k) * N + n];
;     }
;     sm[k * 65 + tx] = v;
;   }
.LBB0_68:
	s_ashr_i32 s6, s3, 31
	s_lshr_b32 s6, s6, 28
	s_add_i32 s6, s3, s6
	s_and_b32 s7, s6, 0x3fffff0
	s_sub_i32 s7, s3, s7
	v_mov_b32_e32 v0, v192
	s_lshl_b32 s12, s7, 6
	v_and_b32_e32 v4, 63, v0
	v_ashrrev_i32_e32 v5, 6, v0
	v_or_b32_e32 v2, s12, v4
	s_lshl_b32 s6, s6, 2
	s_andn2_b32 s6, s6, 63
	v_ashrrev_i32_e32 v3, 31, v2
	v_mul_lo_u32 v0, v5, s1
	v_cmp_gt_i32_e32 vcc, s0, v2
	v_lshl_add_u64 v[2:3], v[2:3], 2, s[66:67]
	v_lshl_add_u32 v0, v4, 2, v0
	v_add_u32_e32 v6, s6, v5
	v_mov_b32_e32 v10, 0
	v_mov_b32_e32 v11, 0
	v_mov_b32_e32 v12, 0
	v_mov_b32_e32 v13, 0
	v_mov_b32_e32 v14, 0
	v_mov_b32_e32 v15, 0
	v_mov_b32_e32 v16, 0
	v_mov_b32_e32 v17, 0
	v_mov_b32_e32 v18, 0
	v_mov_b32_e32 v19, 0
	v_mov_b32_e32 v20, 0
	v_mov_b32_e32 v21, 0
	v_mov_b32_e32 v22, 0
	v_mov_b32_e32 v23, 0
	v_mov_b32_e32 v24, 0
	v_mov_b32_e32 v25, 0
	s_and_saveexec_b64 s[100:101], vcc
	s_mov_b32 s98, 0x1000
	v_mad_u64_u32 v[8:9], vcc, v6, s98, v[2:3]
	s_mov_b32 s98, 0x4000
	s_mov_b32 s99, 0
	global_load_dword v10, v[8:9], off
	v_lshl_add_u64 v[8:9], v[8:9], 0, s[98:99]
	global_load_dword v11, v[8:9], off
	v_lshl_add_u64 v[8:9], v[8:9], 0, s[98:99]
	global_load_dword v12, v[8:9], off
	v_lshl_add_u64 v[8:9], v[8:9], 0, s[98:99]
	global_load_dword v13, v[8:9], off
	v_lshl_add_u64 v[8:9], v[8:9], 0, s[98:99]
	global_load_dword v14, v[8:9], off
	v_lshl_add_u64 v[8:9], v[8:9], 0, s[98:99]
	global_load_dword v15, v[8:9], off
	v_lshl_add_u64 v[8:9], v[8:9], 0, s[98:99]
	global_load_dword v16, v[8:9], off
	v_lshl_add_u64 v[8:9], v[8:9], 0, s[98:99]
	global_load_dword v17, v[8:9], off
	v_lshl_add_u64 v[8:9], v[8:9], 0, s[98:99]
	global_load_dword v18, v[8:9], off
	v_lshl_add_u64 v[8:9], v[8:9], 0, s[98:99]
	global_load_dword v19, v[8:9], off
	v_lshl_add_u64 v[8:9], v[8:9], 0, s[98:99]
	global_load_dword v20, v[8:9], off
	v_lshl_add_u64 v[8:9], v[8:9], 0, s[98:99]
	global_load_dword v21, v[8:9], off
	v_lshl_add_u64 v[8:9], v[8:9], 0, s[98:99]
	global_load_dword v22, v[8:9], off
	v_lshl_add_u64 v[8:9], v[8:9], 0, s[98:99]
	global_load_dword v23, v[8:9], off
	v_lshl_add_u64 v[8:9], v[8:9], 0, s[98:99]
	global_load_dword v24, v[8:9], off
	v_lshl_add_u64 v[8:9], v[8:9], 0, s[98:99]
	global_load_dword v25, v[8:9], off
	s_or_b64 exec, exec, s[100:101]
	s_waitcnt vmcnt(0)
	ds_write_b32 v0, v10
	ds_write_b32 v0, v11 offset:1040
	ds_write_b32 v0, v12 offset:2080
	ds_write_b32 v0, v13 offset:3120
	ds_write_b32 v0, v14 offset:4160
	ds_write_b32 v0, v15 offset:5200
	ds_write_b32 v0, v16 offset:6240
	ds_write_b32 v0, v17 offset:7280
	ds_write_b32 v0, v18 offset:8320
	ds_write_b32 v0, v19 offset:9360
	ds_write_b32 v0, v20 offset:10400
	ds_write_b32 v0, v21 offset:11440
	ds_write_b32 v0, v22 offset:12480
	ds_write_b32 v0, v23 offset:13520
	ds_write_b32 v0, v24 offset:14560
	ds_write_b32 v0, v25 offset:15600

; DI int otid() { int t = threadIdx.x; asm volatile("" : "+v"(t)); return t; }
; DI void transpose_tile(const float* __restrict__ W, int K, int N, bf16_t* __restrict__ Wt, int Np, int kt, int nt,
;                        int mode, float* sm) {
;   const int tid = otid();
;   const int tx = tid & 63, ty = tid >> 6;
; #pragma unroll 4
;   for (int i = 0; i < 16; ++i) {
;     int k = ty + 4 * i;
;     int np = nt * 64 + tx;
;     float v = 0.f;
;     if (np < Np) {
;       int n = mode ? winmap(np) : np;
;       v = W[(size_t)(kt * 64 + k) * N + n];
;     }
;     sm[k * 65 + tx] = v;
;   }
.LBB0_91:
	s_ashr_i32 s10, s3, 31
	s_lshr_b32 s10, s10, 27
	s_add_i32 s10, s3, s10
	s_and_b32 s11, s10, 0x3ffffe0
	s_sub_i32 s11, s3, s11
	v_mov_b32_e32 v0, v192
	s_lshl_b32 s14, s11, 6
	v_and_b32_e32 v4, 63, v0
	v_ashrrev_i32_e32 v5, 6, v0
	v_or_b32_e32 v2, s14, v4
	s_lshl_b32 s10, s10, 1
	s_andn2_b32 s10, s10, 63
	v_ashrrev_i32_e32 v3, 31, v2
	v_mul_lo_u32 v0, v5, s1
	v_cmp_gt_i32_e32 vcc, s0, v2
	v_lshl_add_u64 v[2:3], v[2:3], 2, s[36:37]
	v_lshl_add_u32 v0, v4, 2, v0
	v_add_u32_e32 v6, s10, v5
	v_mov_b32_e32 v10, 0
	v_mov_b32_e32 v11, 0
	v_mov_b32_e32 v12, 0
	v_mov_b32_e32 v13, 0
	v_mov_b32_e32 v14, 0
	v_mov_b32_e32 v15, 0
	v_mov_b32_e32 v16, 0
	v_mov_b32_e32 v17, 0
	v_mov_b32_e32 v18, 0
	v_mov_b32_e32 v19, 0
	v_mov_b32_e32 v20, 0
	v_mov_b32_e32 v21, 0
	v_mov_b32_e32 v22, 0
	v_mov_b32_e32 v23, 0
	v_mov_b32_e32 v24, 0
	v_mov_b32_e32 v25, 0
	s_and_saveexec_b64 s[100:101], vcc
	s_mov_b32 s98, 0x2000
	v_mad_u64_u32 v[8:9], vcc, v6, s98, v[2:3]
	s_mov_b32 s98, 0x8000
	s_mov_b32 s99, 0
	global_load_dword v10, v[8:9], off
	v_lshl_add_u64 v[8:9], v[8:9], 0, s[98:99]
	global_load_dword v11, v[8:9], off
	v_lshl_add_u64 v[8:9], v[8:9], 0, s[98:99]
	global_load_dword v12, v[8:9], off
	v_lshl_add_u64 v[8:9], v[8:9], 0, s[98:99]
	global_load_dword v13, v[8:9], off
	v_lshl_add_u64 v[8:9], v[8:9], 0, s[98:99]
	global_load_dword v14, v[8:9], off
	v_lshl_add_u64 v[8:9], v[8:9], 0, s[98:99]
	global_load_dword v15, v[8:9], off
	v_lshl_add_u64 v[8:9], v[8:9], 0, s[98:99]
	global_load_dword v16, v[8:9], off
	v_lshl_add_u64 v[8:9], v[8:9], 0, s[98:99]
	global_load_dword v17, v[8:9], off
	v_lshl_add_u64 v[8:9], v[8:9], 0, s[98:99]
	global_load_dword v18, v[8:9], off
	v_lshl_add_u64 v[8:9], v[8:9], 0, s[98:99]
	global_load_dword v19, v[8:9], off
	v_lshl_add_u64 v[8:9], v[8:9], 0, s[98:99]
	global_load_dword v20, v[8:9], off
	v_lshl_add_u64 v[8:9], v[8:9], 0, s[98:99]
	global_load_dword v21, v[8:9], off
	v_lshl_add_u64 v[8:9], v[8:9], 0, s[98:99]
	global_load_dword v22, v[8:9], off
	v_lshl_add_u64 v[8:9], v[8:9], 0, s[98:99]
	global_load_dword v23, v[8:9], off
	v_lshl_add_u64 v[8:9], v[8:9], 0, s[98:99]
	global_load_dword v24, v[8:9], off
	v_lshl_add_u64 v[8:9], v[8:9], 0, s[98:99]
	global_load_dword v25, v[8:9], off
	s_or_b64 exec, exec, s[100:101]
	s_waitcnt vmcnt(0)
	ds_write_b32 v0, v10
	ds_write_b32 v0, v11 offset:1040
	ds_write_b32 v0, v12 offset:2080
	ds_write_b32 v0, v13 offset:3120
	ds_write_b32 v0, v14 offset:4160
	ds_write_b32 v0, v15 offset:5200
	ds_write_b32 v0, v16 offset:6240
	ds_write_b32 v0, v17 offset:7280
	ds_write_b32 v0, v18 offset:8320
	ds_write_b32 v0, v19 offset:9360
	ds_write_b32 v0, v20 offset:10400
	ds_write_b32 v0, v21 offset:11440
	ds_write_b32 v0, v22 offset:12480
	ds_write_b32 v0, v23 offset:13520
	ds_write_b32 v0, v24 offset:14560
	ds_write_b32 v0, v25 offset:15600

; DI int otid() { int t = threadIdx.x; asm volatile("" : "+v"(t)); return t; }
; DI void transpose_tile(const float* __restrict__ W, int K, int N, bf16_t* __restrict__ Wt, int Np, int kt, int nt,
;                        int mode, float* sm) {
;   const int tid = otid();
;   const int tx = tid & 63, ty = tid >> 6;
; #pragma unroll 4
;   for (int i = 0; i < 16; ++i) {
;     int k = ty + 4 * i;
;     int np = nt * 64 + tx;
;     float v = 0.f;
;     if (np < Np) {
;       int n = mode ? winmap(np) : np;
;       v = W[(size_t)(kt * 64 + k) * N + n];
;     }
;     sm[k * 65 + tx] = v;
;   }
.LBB0_114:
	s_ashr_i32 s4, s3, 31
	s_lshr_b32 s4, s4, 28
	s_add_i32 s4, s3, s4
	s_and_b32 s5, s4, 0x3fffff0
	s_sub_i32 s5, s3, s5
	v_mov_b32_e32 v0, v192
	s_lshl_b32 s12, s5, 6
	v_and_b32_e32 v4, 63, v0
	v_ashrrev_i32_e32 v5, 6, v0
	v_or_b32_e32 v2, s12, v4
	s_lshl_b32 s4, s4, 2
	s_andn2_b32 s4, s4, 63
	v_ashrrev_i32_e32 v3, 31, v2
	v_mul_lo_u32 v0, v5, s1
	v_cmp_gt_i32_e32 vcc, s0, v2
	v_lshl_add_u64 v[2:3], v[2:3], 2, s[38:39]
	v_lshl_add_u32 v0, v4, 2, v0
	v_add_u32_e32 v6, s4, v5
	v_mov_b32_e32 v10, 0
	v_mov_b32_e32 v11, 0
	v_mov_b32_e32 v12, 0
	v_mov_b32_e32 v13, 0
	v_mov_b32_e32 v14, 0
	v_mov_b32_e32 v15, 0
	v_mov_b32_e32 v16, 0
	v_mov_b32_e32 v17, 0
	v_mov_b32_e32 v18, 0
	v_mov_b32_e32 v19, 0
	v_mov_b32_e32 v20, 0
	v_mov_b32_e32 v21, 0
	v_mov_b32_e32 v22, 0
	v_mov_b32_e32 v23, 0
	v_mov_b32_e32 v24, 0
	v_mov_b32_e32 v25, 0
	s_and_saveexec_b64 s[100:101], vcc
	s_mov_b32 s98, 0x1000
	v_mad_u64_u32 v[8:9], vcc, v6, s98, v[2:3]
	s_mov_b32 s98, 0x4000
	s_mov_b32 s99, 0
	global_load_dword v10, v[8:9], off
	v_lshl_add_u64 v[8:9], v[8:9], 0, s[98:99]
	global_load_dword v11, v[8:9], off
	v_lshl_add_u64 v[8:9], v[8:9], 0, s[98:99]
	global_load_dword v12, v[8:9], off
	v_lshl_add_u64 v[8:9], v[8:9], 0, s[98:99]
	global_load_dword v13, v[8:9], off
	v_lshl_add_u64 v[8:9], v[8:9], 0, s[98:99]
	global_load_dword v14, v[8:9], off
	v_lshl_add_u64 v[8:9], v[8:9], 0, s[98:99]
	global_load_dword v15, v[8:9], off
	v_lshl_add_u64 v[8:9], v[8:9], 0, s[98:99]
	global_load_dword v16, v[8:9], off
	v_lshl_add_u64 v[8:9], v[8:9], 0, s[98:99]
	global_load_dword v17, v[8:9], off
	v_lshl_add_u64 v[8:9], v[8:9], 0, s[98:99]
	global_load_dword v18, v[8:9], off
	v_lshl_add_u64 v[8:9], v[8:9], 0, s[98:99]
	global_load_dword v19, v[8:9], off
	v_lshl_add_u64 v[8:9], v[8:9], 0, s[98:99]
	global_load_dword v20, v[8:9], off
	v_lshl_add_u64 v[8:9], v[8:9], 0, s[98:99]
	global_load_dword v21, v[8:9], off
	v_lshl_add_u64 v[8:9], v[8:9], 0, s[98:99]
	global_load_dword v22, v[8:9], off
	v_lshl_add_u64 v[8:9], v[8:9], 0, s[98:99]
	global_load_dword v23, v[8:9], off
	v_lshl_add_u64 v[8:9], v[8:9], 0, s[98:99]
	global_load_dword v24, v[8:9], off
	v_lshl_add_u64 v[8:9], v[8:9], 0, s[98:99]
	global_load_dword v25, v[8:9], off
	s_or_b64 exec, exec, s[100:101]
	s_waitcnt vmcnt(0)
	ds_write_b32 v0, v10
	ds_write_b32 v0, v11 offset:1040
	ds_write_b32 v0, v12 offset:2080
	ds_write_b32 v0, v13 offset:3120
	ds_write_b32 v0, v14 offset:4160
	ds_write_b32 v0, v15 offset:5200
	ds_write_b32 v0, v16 offset:6240
	ds_write_b32 v0, v17 offset:7280
	ds_write_b32 v0, v18 offset:8320
	ds_write_b32 v0, v19 offset:9360
	ds_write_b32 v0, v20 offset:10400
	ds_write_b32 v0, v21 offset:11440
	ds_write_b32 v0, v22 offset:12480
	ds_write_b32 v0, v23 offset:13520
	ds_write_b32 v0, v24 offset:14560
	ds_write_b32 v0, v25 offset:15600

; DI int otid() { int t = threadIdx.x; asm volatile("" : "+v"(t)); return t; }
; DI void transpose_tile(const float* __restrict__ W, int K, int N, bf16_t* __restrict__ Wt, int Np, int kt, int nt,
;                        int mode, float* sm) {
;   const int tid = otid();
;   const int tx = tid & 63, ty = tid >> 6;
; #pragma unroll 4
;   for (int i = 0; i < 16; ++i) {
;     int k = ty + 4 * i;
;     int np = nt * 64 + tx;
;     float v = 0.f;
;     if (np < Np) {
;       int n = mode ? winmap(np) : np;
;       v = W[(size_t)(kt * 64 + k) * N + n];
;     }
;     sm[k * 65 + tx] = v;
;   }
.LBB0_137:
	s_ashr_i32 s4, s3, 31
	s_lshr_b32 s4, s4, 27
	s_add_i32 s5, s3, s4
	s_and_b32 s4, s5, 0x3ffffe0
	s_sub_i32 s4, s3, s4
	v_mov_b32_e32 v0, v192
	s_lshl_b32 s4, s4, 6
	v_and_b32_e32 v4, 63, v0
	v_ashrrev_i32_e32 v5, 6, v0
	v_or_b32_e32 v2, s4, v4
	s_lshl_b32 s5, s5, 1
	s_and_b32 s6, s5, 0xffffffc0
	v_ashrrev_i32_e32 v3, 31, v2
	v_mul_lo_u32 v0, v5, s1
	v_cmp_gt_i32_e32 vcc, s0, v2
	v_lshl_add_u64 v[2:3], v[2:3], 2, s[42:43]
	v_lshl_add_u32 v0, v4, 2, v0
	v_add_u32_e32 v6, s6, v5
	v_mov_b32_e32 v10, 0
	v_mov_b32_e32 v11, 0
	v_mov_b32_e32 v12, 0
	v_mov_b32_e32 v13, 0
	v_mov_b32_e32 v14, 0
	v_mov_b32_e32 v15, 0
	v_mov_b32_e32 v16, 0
	v_mov_b32_e32 v17, 0
	v_mov_b32_e32 v18, 0
	v_mov_b32_e32 v19, 0
	v_mov_b32_e32 v20, 0
	v_mov_b32_e32 v21, 0
	v_mov_b32_e32 v22, 0
	v_mov_b32_e32 v23, 0
	v_mov_b32_e32 v24, 0
	v_mov_b32_e32 v25, 0
	s_and_saveexec_b64 s[100:101], vcc
	s_mov_b32 s98, 0x2000
	v_mad_u64_u32 v[8:9], vcc, v6, s98, v[2:3]
	s_mov_b32 s98, 0x8000
	s_mov_b32 s99, 0
	global_load_dword v10, v[8:9], off
	v_lshl_add_u64 v[8:9], v[8:9], 0, s[98:99]
	global_load_dword v11, v[8:9], off
	v_lshl_add_u64 v[8:9], v[8:9], 0, s[98:99]
	global_load_dword v12, v[8:9], off
	v_lshl_add_u64 v[8:9], v[8:9], 0, s[98:99]
	global_load_dword v13, v[8:9], off
	v_lshl_add_u64 v[8:9], v[8:9], 0, s[98:99]
	global_load_dword v14, v[8:9], off
	v_lshl_add_u64 v[8:9], v[8:9], 0, s[98:99]
	global_load_dword v15, v[8:9], off
	v_lshl_add_u64 v[8:9], v[8:9], 0, s[98:99]
	global_load_dword v16, v[8:9], off
	v_lshl_add_u64 v[8:9], v[8:9], 0, s[98:99]
	global_load_dword v17, v[8:9], off
	v_lshl_add_u64 v[8:9], v[8:9], 0, s[98:99]
	global_load_dword v18, v[8:9], off
	v_lshl_add_u64 v[8:9], v[8:9], 0, s[98:99]
	global_load_dword v19, v[8:9], off
	v_lshl_add_u64 v[8:9], v[8:9], 0, s[98:99]
	global_load_dword v20, v[8:9], off
	v_lshl_add_u64 v[8:9], v[8:9], 0, s[98:99]
	global_load_dword v21, v[8:9], off
	v_lshl_add_u64 v[8:9], v[8:9], 0, s[98:99]
	global_load_dword v22, v[8:9], off
	v_lshl_add_u64 v[8:9], v[8:9], 0, s[98:99]
	global_load_dword v23, v[8:9], off
	v_lshl_add_u64 v[8:9], v[8:9], 0, s[98:99]
	global_load_dword v24, v[8:9], off
	v_lshl_add_u64 v[8:9], v[8:9], 0, s[98:99]
	global_load_dword v25, v[8:9], off
	s_or_b64 exec, exec, s[100:101]
	s_waitcnt vmcnt(0)
	ds_write_b32 v0, v10
	ds_write_b32 v0, v11 offset:1040
	ds_write_b32 v0, v12 offset:2080
	ds_write_b32 v0, v13 offset:3120
	ds_write_b32 v0, v14 offset:4160
	ds_write_b32 v0, v15 offset:5200
	ds_write_b32 v0, v16 offset:6240
	ds_write_b32 v0, v17 offset:7280
	ds_write_b32 v0, v18 offset:8320
	ds_write_b32 v0, v19 offset:9360
	ds_write_b32 v0, v20 offset:10400
	ds_write_b32 v0, v21 offset:11440
	ds_write_b32 v0, v22 offset:12480
	ds_write_b32 v0, v23 offset:13520
	ds_write_b32 v0, v24 offset:14560
	ds_write_b32 v0, v25 offset:15600

; __global__ void __launch_bounds__(256, 2) hymba_mega(Params p) {
;   cg::grid_group grid = cg::this_grid();
;   __shared__ __attribute__((aligned(16))) char smem[SMEM_BYTES];
	.amdhsa_kernel _Z10hymba_mega6Params
		.amdhsa_group_segment_fixed_size 77840
		.amdhsa_private_segment_fixed_size 0
		.amdhsa_kernarg_size 464
		.amdhsa_user_sgpr_count 2
		.amdhsa_user_sgpr_dispatch_ptr 0
		.amdhsa_user_sgpr_queue_ptr 0
		.amdhsa_user_sgpr_kernarg_segment_ptr 1
		.amdhsa_user_sgpr_dispatch_id 0
		.amdhsa_user_sgpr_kernarg_preload_length 0
		.amdhsa_user_sgpr_kernarg_preload_offset 0
		.amdhsa_user_sgpr_private_segment_size 0
		.amdhsa_uses_dynamic_stack 0
		.amdhsa_enable_private_segment 0
		.amdhsa_system_sgpr_workgroup_id_x 1
		.amdhsa_system_sgpr_workgroup_id_y 0
		.amdhsa_system_sgpr_workgroup_id_z 0
		.amdhsa_system_sgpr_workgroup_info 0
		.amdhsa_system_vgpr_workitem_id 2
		.amdhsa_next_free_vgpr 231
		.amdhsa_next_free_sgpr 102
		.amdhsa_accum_offset 232
		.amdhsa_reserve_vcc 1
		.amdhsa_float_round_mode_32 0
		.amdhsa_float_round_mode_16_64 0
		.amdhsa_float_denorm_mode_32 3
		.amdhsa_float_denorm_mode_16_64 3
		.amdhsa_dx10_clamp 1
		.amdhsa_ieee_mode 1
		.amdhsa_fp16_overflow 0
		.amdhsa_tg_split 0
		.amdhsa_exception_fp_ieee_invalid_op 0
		.amdhsa_exception_fp_denorm_src 0
		.amdhsa_exception_fp_ieee_div_zero 0
		.amdhsa_exception_fp_ieee_overflow 0
		.amdhsa_exception_fp_ieee_underflow 0
		.amdhsa_exception_fp_ieee_inexact 0
		.amdhsa_exception_int_div_zero 0
	.end_amdhsa_kernel

; __global__ void __launch_bounds__(256, 2) hymba_mega(Params p) {
;   cg::grid_group grid = cg::this_grid();
;   __shared__ __attribute__((aligned(16))) char smem[SMEM_BYTES];
amdhsa.kernels:
  - .agpr_count:     0
    .args:
      - .offset:         0
        .size:           208
        .value_kind:     by_value
      - .offset:         208
        .size:           4
        .value_kind:     hidden_block_count_x
      - .offset:         212
        .size:           4
        .value_kind:     hidden_block_count_y
      - .offset:         216
        .size:           4
        .value_kind:     hidden_block_count_z
      - .offset:         220
        .size:           2
        .value_kind:     hidden_group_size_x
      - .offset:         222
        .size:           2
        .value_kind:     hidden_group_size_y
      - .offset:         224
        .size:           2
        .value_kind:     hidden_group_size_z
      - .offset:         226
        .size:           2
        .value_kind:     hidden_remainder_x
      - .offset:         228
        .size:           2
        .value_kind:     hidden_remainder_y
      - .offset:         230
        .size:           2
        .value_kind:     hidden_remainder_z
      - .offset:         248
        .size:           8
        .value_kind:     hidden_global_offset_x
      - .offset:         256
        .size:           8
        .value_kind:     hidden_global_offset_y
      - .offset:         264
        .size:           8
        .value_kind:     hidden_global_offset_z
      - .offset:         272
        .size:           2
        .value_kind:     hidden_grid_dims
      - .offset:         296
        .size:           8
        .value_kind:     hidden_multigrid_sync_arg
    .group_segment_fixed_size: 77840
    .kernarg_segment_align: 8
    .kernarg_segment_size: 464
    .language:       OpenCL C
    .language_version:
      - 2
      - 0
    .max_flat_workgroup_size: 256
    .name:           _Z10hymba_mega6Params
    .private_segment_fixed_size: 0
    .sgpr_count:     108
    .sgpr_spill_count: 18
    .symbol:         _Z10hymba_mega6Params.kd
    .uniform_work_group_size: 1
    .uses_dynamic_stack: false
    .vgpr_count:     231
    .vgpr_spill_count: 0
    .wavefront_size: 64
